# code placement: cold-spot nop pads so every hot loop head sits at the baseline's byte phase mod 64
# baseline (speedup 1.0000x reference)
.LBB0_301:
.LBB0_302:
	s_xor_b64 s[4:5], s[4:5], -1
	v_writelane_b32 v252, s4, 3
	s_cmp_lt_i32 s20, 3
	s_nop 0
	v_writelane_b32 v252, s5, 4
	s_cselect_b64 s[4:5], -1, 0
	s_cmp_gt_i32 s21, 2
	s_cselect_b64 s[6:7], -1, 0
	s_and_b64 s[4:5], s[4:5], s[6:7]
	s_andn2_b64 vcc, exec, s[4:5]
	s_cbranch_vccnz .LBB0_640
	s_nop 0
	s_nop 0
	s_nop 0
	s_nop 0
	s_nop 0
	s_nop 0
	s_nop 0
	s_nop 0
	s_nop 0
	s_nop 0
	s_nop 0
	s_mov_b64 s[4:5], s[0:1]
	v_mov_b32_e32 v0, v244
	s_load_dwordx2 s[6:7], s[4:5], 0xa8
	v_add_u32_e32 v0, s76, v0
	s_waitcnt vmcnt(0)
	v_ashrrev_i32_e32 v1, 31, v0
	s_mov_b64 s[4:5], s[0:1]
	s_waitcnt lgkmcnt(0)
	v_lshl_add_u64 v[2:3], v[0:1], 2, s[6:7]
	v_add_co_u32_e32 v4, vcc, 0x136000, v2
	s_movk_i32 s3, 0x80
	s_nop 0
	v_addc_co_u32_e32 v5, vcc, 0, v3, vcc
	v_add_co_u32_e32 v6, vcc, 0x137000, v2
	s_nop 1
	v_addc_co_u32_e32 v7, vcc, 0, v3, vcc
	v_add_co_u32_e32 v8, vcc, 0x138000, v2
	s_nop 1
	v_addc_co_u32_e32 v9, vcc, 0, v3, vcc
	global_load_dword v10, v[4:5], off
	global_load_dword v11, v[4:5], off offset:2048
	global_load_dword v12, v[6:7], off
	global_load_dword v13, v[6:7], off offset:2048
	global_load_dword v1, v[8:9], off
	global_load_dword v2, v[8:9], off offset:2048
	v_lshl_add_u32 v3, v0, 2, 0
	v_add_u32_e32 v3, 0x20000, v3
	v_cmp_gt_i32_e32 vcc, s3, v0
	s_waitcnt vmcnt(4)
	ds_write2st64_b32 v3, v10, v11 offset1:8
	s_waitcnt vmcnt(2)
	ds_write2st64_b32 v3, v12, v13 offset0:16 offset1:24
	s_and_saveexec_b64 s[6:7], vcc
	s_cbranch_execz .LBB0_305
	s_load_dwordx2 s[4:5], s[4:5], 0x48
	v_and_b32_e32 v0, 0x7f, v0
	v_lshlrev_b32_e32 v0, 2, v0
	s_waitcnt lgkmcnt(0)
	global_load_dword v0, v0, s[4:5]
	s_waitcnt vmcnt(0)
	ds_write_b32 v3, v0 offset:8192

.LBB0_640:
	s_cmp_lt_i32 s20, 4
	s_cselect_b64 s[4:5], -1, 0
	s_cmp_gt_i32 s21, 3
	s_cselect_b64 s[6:7], -1, 0
	s_and_b64 s[4:5], s[4:5], s[6:7]
	s_andn2_b64 vcc, exec, s[4:5]
	s_cbranch_vccnz .LBB0_807
	s_nop 0
	s_nop 0
	s_mov_b64 s[4:5], s[0:1]
	v_mov_b32_e32 v0, v244
	s_load_dwordx2 s[4:5], s[4:5], 0xa8
	v_mov_b32_e32 v0, 0x139000
	s_and_b32 s28, s2, 7
	s_waitcnt lgkmcnt(0)
	global_load_dword v1, v0, s[4:5] sc1
	global_load_dword v2, v0, s[4:5] offset:4 sc1
	s_bfe_u32 s3, s74, 0x20006
	s_lshl_b32 s8, s75, 7
	s_sub_i32 s9, s33, s28
	s_lshl_b32 s10, s3, 5
	s_lshl_b32 s65, s3, 4
	s_add_i32 s79, s8, 0
	s_lshl_b32 s3, s3, 14
	s_add_i32 s8, s9, 7
	s_add_i32 s80, s3, 0
	s_ashr_i32 s3, s8, 31
	s_lshl_b32 s7, s75, 11
	s_lshr_b32 s3, s3, 29
	s_lshr_b32 s6, s74, 8
	s_add_i32 s67, s7, 0
	s_add_i32 s8, s8, s3
	s_ashr_i32 s29, s2, 3
	s_lshl_b32 s64, s75, 4
	s_lshl_b32 s31, s28, 6
	s_lshl_b32 s66, s6, 6
	s_lshl_b32 s68, s6, 13
	s_lshl_b32 s69, s6, 4
	s_add_i32 s70, s67, 0x4000
	s_add_i32 s71, s67, 0x8000
	s_add_i32 s72, s67, 0x8400
	s_add_i32 s73, s67, 0xc000
	s_add_i32 s78, s67, 0xc400
	s_add_i32 s79, s79, 0x20000
	s_add_i32 s80, s80, 0x10000
	s_ashr_i32 s3, s8, 3
	s_cmpk_lt_u32 s74, 0x100
	s_cselect_b64 s[46:47], -1, 0
	s_cmp_eq_u32 s6, 1
	v_writelane_b32 v252, s24, 5
	s_cselect_b64 s[48:49], -1, 0
	s_lshl_b32 s6, s75, 5
	s_and_b32 s82, s75, 0x3fffffc
	s_and_b32 s83, s64, 0x3fffffc0
	v_writelane_b32 v252, s25, 6
	s_mov_b64 s[24:25], s[84:85]
	s_lshl_b32 s81, s28, 3
	s_or_b32 s84, s75, 3
	s_and_b32 s85, s6, 0x60
	s_or_b32 s86, s82, 1
	s_or_b32 s87, s82, 2
	s_or_b32 s88, s83, 32
	s_cmp_lt_u32 s74, 64
	s_mul_i32 s7, s28, 0x120000
	s_cselect_b64 s[44:45], -1, 0
	s_lshl_b32 s62, s28, 11
	s_mov_b32 s35, 0
	s_movk_i32 s63, 0xc8
	s_mov_b64 s[4:5], -1
	s_mov_b64 s[36:37], 0x10000
	s_movk_i32 s30, 0x1200
	v_mov_b32_e32 v145, 0
	s_mov_b64 s[38:39], 0x80
	s_mov_b64 s[40:41], 0x20000
	s_mov_b64 s[42:43], 0x100
	v_mov_b32_e32 v147, 1
	s_lshl_b32 s51, s28, 9
	s_add_i32 s89, 0, 0x27c40
	s_or_b32 s90, s62, s10
	s_add_i32 s91, 0, 0x19000
	s_add_i32 s92, 0, 0x1a000
	s_add_i32 s93, 0, 0x1b000
	s_brev_b32 s50, 60
	s_mov_b32 s94, 0x800000
	v_mov_b32_e32 v151, 0x20000
	s_lshl_b32 s95, s7, 1
	v_mov_b32_e32 v155, 0x1200
	s_waitcnt vmcnt(0)
	v_cndmask_b32_e64 v149, v1, 1.0, s[46:47]
	v_xor_b32_e32 v0, 0x80000000, v2
	v_mov_b32_e32 v1, v0
	v_mov_b32_e32 v2, v0
	v_mov_b32_e32 v3, v0
	v_mov_b32_e32 v4, v0
	v_mov_b32_e32 v5, v0
	v_mov_b32_e32 v6, v0
	v_mov_b32_e32 v7, v0
	v_mov_b32_e32 v8, v0
	v_mov_b32_e32 v9, v0
	v_mov_b32_e32 v10, v0
	v_mov_b32_e32 v11, v0
	v_mov_b32_e32 v12, v0
	v_mov_b32_e32 v13, v0
	v_mov_b32_e32 v14, v0
	v_mov_b32_e32 v15, v0
	s_branch .LBB0_644

.LBB0_700:
	s_nop 0
	s_nop 0
	s_nop 0
	s_nop 0
	s_nop 0
	s_nop 0
	s_nop 0
	s_nop 0
	s_nop 0
	s_nop 0
	s_nop 0
	s_lshl_b32 s6, s31, 2
	s_waitcnt lgkmcnt(0)
	s_add_u32 s4, s4, s6
	s_addc_u32 s5, s5, 0
	s_add_u32 s12, s4, 0x10000
	s_addc_u32 s13, s5, 0
	s_and_b32 s4, s75, 1
	s_lshr_b32 s5, s74, 7
	s_lshl_b32 s30, s4, 2
	s_lshl_b32 s6, s5, 8
	s_lshl_b32 s31, s4, 5
	s_lshl_b32 s47, s5, 5
	s_or_b32 s48, s30, 2
	s_cmp_eq_u32 s4, 0
	v_mov_b32_e32 v34, v32
	v_mov_b32_e32 v35, v32
	s_cselect_b64 s[14:15], -1, 0
	s_cmp_eq_u32 s4, 1
	v_mov_b32_e32 v33, v32
	s_mov_b32 s11, 0
	s_cselect_b64 s[16:17], -1, 0
	s_add_i32 s49, s6, 0
	v_cndmask_b32_e64 v0, 0, 1, s[44:45]
	v_mov_b64_e32 v[54:55], v[34:35]
	v_mov_b64_e32 v[50:51], v[34:35]
	v_mov_b64_e32 v[46:47], v[34:35]
	v_mov_b64_e32 v[42:43], v[34:35]
	v_mov_b64_e32 v[38:39], v[34:35]
	s_mov_b32 s46, s11
	s_add_i32 s49, s49, 0x26000
	s_lshl_b32 s50, s28, 2
	s_add_i32 s52, s29, 0x4800
	s_lshl_b32 s28, s28, 23
	s_xor_b32 s53, s30, 4
	s_xor_b32 s54, s30, 6
	s_mov_b64 s[40:41], 0
	v_cmp_ne_u32_e64 s[4:5], 1, v0
	s_mov_b64 s[18:19], 0x1800000
	s_mov_b64 s[34:35], 0xac00000
	s_movk_i32 s44, 0x1200
	s_mov_b64 s[36:37], 0x5800400
	s_mov_b32 s45, 0x5800000
	s_mov_b32 s55, 0x5801000
	s_movk_i32 s56, 0x1000
	s_mov_b32 s57, 0x5802000
	s_mov_b32 s58, 0x5803000
	v_mov_b32_e32 v206, 1
	s_add_i32 s59, 0, 0x24000
	s_mov_b32 s60, 0xc2c80000
	s_add_i32 s61, 0, 0x10000
	s_add_i32 s64, 0, 0x18000
	s_add_i32 s65, 0, 0x20000
	s_add_i32 s66, 0, 0x27c40
	s_mov_b32 s67, 0xe200000
	s_mov_b64 s[38:39], 0x1880000
	v_mov_b32_e32 v207, 0x358637bd
	s_mov_b32 s68, 0x800000
	s_movk_i32 s69, 0x210
	v_mov_b32_e32 v208, 0x42c80000
	v_mov_b64_e32 v[52:53], v[32:33]
	v_mov_b64_e32 v[48:49], v[32:33]
	v_mov_b64_e32 v[44:45], v[32:33]
	v_mov_b64_e32 v[40:41], v[32:33]
	v_mov_b64_e32 v[36:37], v[32:33]
	s_mov_b32 s70, 0
	v_mov_b32_e32 v64, v32
	v_mov_b32_e32 v63, v32
	v_mov_b32_e32 v68, v32
	v_mov_b32_e32 v69, v32
	v_mov_b32_e32 v56, v32
	v_mov_b32_e32 v59, v32
	v_mov_b32_e32 v62, v32
	v_mov_b32_e32 v61, v32
	v_mov_b32_e32 v66, v32
	v_mov_b32_e32 v65, v32
	v_mov_b32_e32 v70, v32
	v_mov_b32_e32 v71, v32
	v_mov_b32_e32 v72, v32
	v_mov_b32_e32 v73, v32
	v_mov_b32_e32 v76, v32
	v_mov_b32_e32 v77, v32
	v_mov_b32_e32 v58, v32
	v_mov_b32_e32 v67, v32
	v_mov_b32_e32 v60, v32
	v_mov_b32_e32 v57, v32
	v_mov_b32_e32 v74, v32
	v_mov_b32_e32 v75, v32
	v_mov_b32_e32 v78, v32
	v_mov_b32_e32 v79, v32
	s_barrier
	s_branch .LBB0_702

.LBB0_807:
	s_cmp_lt_i32 s20, 6
	s_cselect_b64 s[4:5], -1, 0
	s_cmp_gt_i32 s21, 5
	s_cselect_b64 s[6:7], -1, 0
	s_and_b64 s[4:5], s[4:5], s[6:7]
	s_andn2_b64 vcc, exec, s[4:5]
	s_cbranch_vccnz .LBB0_918
	s_nop 0
	s_nop 0
	s_nop 0
	s_nop 0
	s_nop 0
	s_nop 0
	s_nop 0
	s_cmpk_lt_i32 s2, 0x100
	s_mov_b64 s[4:5], s[0:1]
	v_mov_b32_e32 v0, v244
	s_cselect_b64 s[6:7], -1, 0
	s_cmpk_gt_i32 s2, 0xff
	s_waitcnt vmcnt(0)
	v_mov_b32_e32 v8, v244
	s_cbranch_scc1 .LBB0_810
	s_ashr_i32 s3, s2, 31
	s_lshr_b32 s3, s3, 29
	s_add_i32 s3, s2, s3
	s_and_b32 s4, s3, -8
	s_sub_i32 s10, s2, s4
	s_lshl_b32 s4, s10, 5
	s_ashr_i32 s3, s3, 3
	s_add_i32 s3, s4, s3
	s_ashr_i32 s4, s3, 31
	s_lshr_b32 s4, s4, 27
	s_add_i32 s4, s3, s4
	s_and_b32 s4, s4, 0xffe0
	s_sub_i32 s3, s3, s4
	s_bfe_i32 s4, s3, 0x80000
	s_bfe_u32 s4, s4, 0x3000c
	s_add_i32 s11, s3, s4
	s_bfe_i32 s4, s11, 0x80000
	s_sext_i32_i16 s14, s4
	s_lshr_b32 s4, s14, 3
	s_bfe_i64 s[4:5], s[4:5], 0x100000
	s_lshl_b64 s[8:9], s[4:5], 19
	s_and_b32 s4, s11, 0xf8
	s_sub_i32 s3, s3, s4
	s_mov_b64 s[4:5], s[0:1]
	s_lshl_b32 s12, s10, 3
	s_load_dwordx2 s[10:11], s[4:5], 0xa8
	s_sext_i32_i8 s3, s3
	s_add_i32 s4, s12, s3
	s_ashr_i32 s5, s4, 31
	s_lshl_b64 s[12:13], s[4:5], 19
	s_ashr_i32 s90, s14, 3
	s_waitcnt lgkmcnt(0)
	s_add_u32 s3, s10, s12
	s_addc_u32 s5, s11, s13
	s_add_u32 s68, s3, 0x5800000
	s_addc_u32 s69, s5, 0
	s_add_u32 s3, s10, s8
	s_addc_u32 s5, s11, s9
	s_add_u32 s70, s3, 0xb00000
	s_addc_u32 s71, s5, 0
	s_andn2_b64 vcc, exec, s[6:7]
	s_cbranch_vccz .LBB0_811
	s_branch .LBB0_842

.LBB0_918:
	s_cmp_lt_i32 s20, 7
	s_cselect_b64 s[4:5], -1, 0
	s_cmp_gt_i32 s21, 6
	s_cselect_b64 s[6:7], -1, 0
	s_and_b64 s[4:5], s[4:5], s[6:7]
	s_andn2_b64 vcc, exec, s[4:5]
	s_cbranch_vccnz .LBB0_1426
	s_nop 0
	s_nop 0
	s_nop 0
	s_nop 0
	s_nop 0
	s_nop 0
	s_nop 0
	s_nop 0
	s_nop 0
	s_nop 0
	s_mov_b64 s[4:5], s[0:1]
	v_mov_b32_e32 v0, v244
	s_load_dwordx2 s[10:11], s[4:5], 0xa8
	s_cmp_gt_u32 s74, 63
	s_cbranch_scc1 .LBB0_929
	s_waitcnt lgkmcnt(0)
	s_add_u32 s4, s10, 0x28300
	s_addc_u32 s5, s11, 0
	s_add_u32 s6, s10, 0x28200
	s_addc_u32 s7, s11, 0
	s_mov_b32 s3, 0x3fffff
	s_waitcnt vmcnt(0)
	v_mov_b32_e32 v1, 0
	s_movk_i32 s14, 0x80
	s_branch .LBB0_922

.LBB0_1280:
	s_nop 0
	s_nop 0
	s_nop 0
	s_nop 0
	s_nop 0
	s_lshr_b32 s6, s83, 31
	s_add_i32 s6, s83, s6
	s_and_b32 s6, s6, -2
	v_cndmask_b32_e64 v0, 0, 1, s[16:17]
	s_sub_i32 s35, s83, s6
	v_mov_b32_e32 v8, v244
	v_cmp_ne_u32_e64 s[6:7], 1, v0
	s_andn2_b64 vcc, exec, s[16:17]
	s_cbranch_vccnz .LBB0_1282
	s_lshr_b32 s9, s81, 28
	s_mov_b64 s[10:11], s[0:1]
	s_add_i32 s9, s2, s9
	s_lshl_b32 s8, s82, 4
	s_ashr_i32 s9, s9, 4
	s_load_dwordx2 s[10:11], s[10:11], 0xa8
	s_add_i32 s54, s8, s9
	s_ashr_i32 s18, s54, 4
	s_add_i32 s8, s35, 12
	s_mov_b32 s9, 0
	s_ashr_i32 s55, s54, 31
	s_ashr_i32 s19, s18, 31
	s_lshl_b64 s[8:9], s[8:9], 19
	s_lshl_b64 s[16:17], s[54:55], 18
	s_lshl_b64 s[18:19], s[18:19], 22
	s_waitcnt lgkmcnt(0)
	s_add_u32 s8, s10, s8
	s_addc_u32 s9, s11, s9
	s_add_u32 s52, s8, 0xd00000
	s_addc_u32 s53, s9, 0
	s_add_u32 s8, s10, s16
	s_addc_u32 s9, s11, s17
	s_add_u32 s8, s8, s18
	s_addc_u32 s9, s9, s19
	s_add_u32 s56, s8, 0x1800000
	s_addc_u32 s57, s9, 0
	s_and_b64 vcc, exec, s[6:7]
	s_cbranch_vccz .LBB0_1283
	s_branch .LBB0_1350

.LBB0_1508:
.LBB0_1509:
	s_cmp_lt_i32 s20, 9
	s_cselect_b64 s[4:5], -1, 0
	s_cmp_gt_i32 s21, 8
	s_cselect_b64 s[6:7], -1, 0
	s_and_b64 s[4:5], s[4:5], s[6:7]
	s_andn2_b64 vcc, exec, s[4:5]
	s_cbranch_vccnz .LBB0_1526
	s_nop 0
	s_nop 0
	s_nop 0
	s_nop 0
	s_nop 0
	s_nop 0
	s_nop 0
	s_nop 0
	s_nop 0
	s_nop 0
	s_nop 0
	s_nop 0
	s_mov_b64 s[4:5], s[0:1]
	v_mov_b32_e32 v0, v244
	s_waitcnt vmcnt(0)
	v_mov_b32_e32 v9, v244
	s_cmpk_gt_i32 s2, 0xff
	s_cbranch_scc1 .LBB0_1526
	s_lshl_b32 s3, s75, 10
	v_lshl_add_u32 v0, v9, 4, s3
	s_waitcnt lgkmcnt(0)
	v_add_u32_e32 v1, 0x2000, v0
	v_ashrrev_i32_e32 v2, 31, v1
	v_lshrrev_b32_e32 v2, 22, v2
	v_add_u32_e32 v2, v1, v2
	v_ashrrev_i32_e32 v8, 10, v2
	v_mul_i32_i24_e32 v2, 0x400, v8
	v_sub_u32_e32 v1, v1, v2
	v_lshrrev_b32_e32 v2, 4, v1
	v_bitop3_b32 v1, v2, v1, 32 bitop3:0x6c
	v_ashrrev_i32_e32 v2, 31, v1
	v_lshrrev_b32_e32 v2, 26, v2
	v_add_u32_e32 v2, v1, v2
	v_ashrrev_i32_e32 v10, 6, v2
	v_lshlrev_b32_e32 v3, 3, v8
	v_and_b32_e32 v2, 0xffc0, v2
	v_and_b32_e32 v3, -16, v3
	v_sub_u32_e32 v1, v1, v2
	v_add_u32_e32 v3, v10, v3
	v_lshrrev_b16_e32 v2, 7, v1
	v_and_b32_e32 v4, 3, v10
	s_mov_b32 s4, 0x1fffe0
	v_lshrrev_b32_e32 v5, 2, v3
	v_lshlrev_b32_e32 v6, 1, v3
	v_and_b32_e32 v2, 1, v2
	v_and_or_b32 v4, v3, s4, v4
	v_and_b32_e32 v5, 4, v5
	v_and_b32_e32 v6, 24, v6
	v_add_u16_e32 v1, v1, v2
	v_mov_b32_e32 v2, 1
	v_or3_b32 v4, v4, v5, v6
	v_lshlrev_b32_e32 v5, 5, v8
	v_ashrrev_i16_sdwa v1, v2, sext(v1) dst_sel:DWORD dst_unused:UNUSED_PAD src0_sel:DWORD src1_sel:BYTE_0
	v_and_b32_e32 v5, 32, v5
	v_bfe_i32 v11, v1, 0, 16
	v_add_lshl_u32 v1, v5, v11, 1
	v_lshl_add_u32 v208, v4, 11, v1
	v_lshl_add_u32 v210, v3, 11, v1
	v_ashrrev_i32_e32 v1, 31, v0
	v_lshrrev_b32_e32 v1, 22, v1
	v_add_u32_e32 v1, v0, v1
	v_ashrrev_i32_e32 v12, 10, v1
	v_mul_i32_i24_e32 v1, 0x400, v12
	v_sub_u32_e32 v0, v0, v1
	v_lshrrev_b32_e32 v1, 4, v0
	v_bitop3_b32 v0, v1, v0, 32 bitop3:0x6c
	v_ashrrev_i32_e32 v1, 31, v0
	v_lshrrev_b32_e32 v1, 26, v1
	v_add_u32_e32 v1, v0, v1
	v_lshlrev_b32_e32 v3, 3, v12
	v_ashrrev_i32_e32 v13, 6, v1
	v_and_b32_e32 v3, -16, v3
	v_add_u32_e32 v3, v13, v3
	v_and_b32_e32 v4, 3, v13
	v_and_or_b32 v4, v3, s4, v4
	s_mov_b64 s[4:5], s[0:1]
	s_load_dwordx2 s[6:7], s[4:5], 0xa8
	s_ashr_i32 s4, s2, 31
	s_lshr_b32 s4, s4, 29
	s_add_i32 s4, s2, s4
	s_ashr_i32 s5, s4, 3
	s_and_b32 s4, s4, -8
	s_sub_i32 s4, s2, s4
	s_lshl_b32 s8, s4, 5
	s_add_i32 s5, s8, s5
	s_ashr_i32 s8, s5, 31
	s_lshr_b32 s8, s8, 27
	s_add_i32 s8, s5, s8
	s_andn2_b32 s8, s8, 31
	s_sub_i32 s5, s5, s8
	s_bfe_i32 s8, s5, 0x80000
	s_bfe_u32 s8, s8, 0x3000c
	s_add_i32 s8, s5, s8
	s_bfe_i32 s9, s8, 0x80000
	s_and_b32 s8, s8, 0xf8
	s_sub_i32 s5, s5, s8
	s_lshl_b32 s4, s4, 3
	s_sext_i32_i8 s5, s5
	s_add_i32 s30, s4, s5
	s_sext_i32_i16 s9, s9
	s_ashr_i32 s31, s30, 31
	s_lshr_b32 s10, s74, 8
	s_lshr_b32 s12, s9, 3
	s_lshl_b64 s[4:5], s[30:31], 19
	s_waitcnt lgkmcnt(0)
	s_add_u32 s11, s6, s4
	s_addc_u32 s13, s7, s5
	s_add_u32 s4, s11, 0x5800000
	s_addc_u32 s5, s13, 0
	s_bfe_i64 s[8:9], s[12:13], 0x100000
	v_lshrrev_b32_e32 v5, 2, v3
	v_lshlrev_b32_e32 v6, 1, v3
	v_and_b32_e32 v1, 0xc0, v1
	s_lshl_b64 s[8:9], s[8:9], 19
	v_and_b32_e32 v5, 4, v5
	v_and_b32_e32 v6, 24, v6
	v_sub_u32_e32 v0, v0, v1
	s_add_u32 s8, s6, s8
	v_or3_b32 v4, v4, v5, v6
	v_lshlrev_b32_e32 v5, 5, v12
	v_ashrrev_i16_sdwa v0, v2, sext(v0) dst_sel:DWORD dst_unused:UNUSED_PAD src0_sel:DWORD src1_sel:BYTE_0
	s_addc_u32 s9, s7, s9
	v_and_b32_e32 v5, 32, v5
	v_bfe_i32 v14, v0, 0, 16
	s_add_u32 s6, s8, 0x1400000
	v_add_lshl_u32 v0, v5, v14, 1
	s_addc_u32 s7, s9, 0
	s_add_i32 s36, s3, 0
	v_lshl_add_u32 v212, v4, 11, v0
	s_add_i32 m0, s36, 0x10000
	v_lshl_add_u32 v214, v3, 11, v0
	global_load_lds_dwordx4 v212, s[6:7]
	s_add_i32 m0, s36, 0x12000
	s_add_u32 s8, s8, 0x1440000
	global_load_lds_dwordx4 v208, s[6:7]
	s_addc_u32 s9, s9, 0
	s_add_i32 m0, s36, 0x14000
	s_add_i32 s37, s36, 0x2000
	global_load_lds_dwordx4 v212, s[8:9]
	s_add_i32 m0, s36, 0x16000
	v_mov_b32_e32 v213, 0
	global_load_lds_dwordx4 v208, s[8:9]
	s_mov_b32 m0, s36
	s_add_u32 s8, s11, 0x5840000
	global_load_lds_dwordx4 v214, s[4:5]
	s_mov_b32 m0, s37
	s_addc_u32 s9, s13, 0
	s_add_i32 s38, s36, 0x4000
	global_load_lds_dwordx4 v210, s[4:5]
	s_mov_b32 m0, s38
	s_add_i32 s39, s36, 0x6000
	global_load_lds_dwordx4 v214, s[8:9]
	s_mov_b32 m0, s39
	v_mov_b32_e32 v209, v213
	global_load_lds_dwordx4 v210, s[8:9]
	v_mov_b32_e32 v215, v213
	v_mov_b32_e32 v211, v213
	s_cmp_eq_u32 s10, 1
	s_mov_b32 s40, 0
	s_mov_b32 s41, 0x10000
	v_lshl_add_u64 v[6:7], s[6:7], 0, v[212:213]
	v_lshl_add_u64 v[4:5], s[6:7], 0, v[208:209]
	v_lshl_add_u64 v[0:1], s[4:5], 0, v[214:215]
	s_cselect_b64 s[8:9], -1, 0
	s_cmp_lg_u32 s10, 1
	v_lshl_add_u64 v[2:3], s[4:5], 0, v[210:211]
	s_cbranch_scc1 .LBB0_1513
	s_barrier
